# weight-conversion bf16 stores non-temporal too (during L0 recurrence)
# speedup vs baseline: 1.0145x; 1.0081x over previous
; #define LAS __attribute__((address_space(3)))
; __device__ __forceinline__ unsigned pk2(float lo, float hi) { f32x2_t v = {lo, hi}; bf16x2_t b = __builtin_convertvector(v, bf16x2_t); return __builtin_bit_cast(unsigned, b); }
; __device__ __forceinline__ void transpose_item(const float* W, int K, int N, bf16* WT, const float* scale, LAS float* scr, int item, int lane) {
;     ...
;         const int q = lane & 7, r = lane >> 3;
;         f32x4 v[8];
; #pragma unroll
;         for (int i = 0; i < 8; ++i) v[i] = *(const f32x4*)(W + (size_t)(k0 + 8 * i + r) * N + n0 + 4 * q);
; #pragma unroll
;         for (int i = 0; i < 8; ++i) { const int kk = 8 * i + r; f32x4 x = v[i]; if (scale) x = x * scale[k0 + kk];
;             scr[kk * 33 + 4 * q + 0] = x[0]; scr[kk * 33 + 4 * q + 1] = x[1]; scr[kk * 33 + 4 * q + 2] = x[2]; scr[kk * 33 + 4 * q + 3] = x[3]; }
;     }
;     asm volatile("s_waitcnt lgkmcnt(0)" ::: "memory");
;     const int c = lane & 7;
; #pragma unroll
;     for (int j = 0; j < 4; ++j) { const int n = (lane >> 3) + 8 * j; const LAS float* s = scr + (8 * c) * 33 + n;
;         v4u o; o.x = pk2(s[0 * 33], s[1 * 33]); o.y = pk2(s[2 * 33], s[3 * 33]); o.z = pk2(s[4 * 33], s[5 * 33]); o.w = pk2(s[6 * 33], s[7 * 33]);
;         *(v4u*)(WT + (size_t)(n0 + n) * K + k0 + 8 * c) = o; }
;     asm volatile("s_waitcnt lgkmcnt(0)" ::: "memory");
.LBB0_1263:
	s_mul_hi_i32 s0, s6, 0x66666667
	s_lshr_b32 s1, s0, 31
	s_ashr_i32 s0, s0, 7
	s_add_i32 s0, s0, s1
	s_lshl_b32 s2, s0, 6
	s_mulk_i32 s0, 0xd800
	s_add_i32 s0, s4, s0
	s_ashr_i32 s1, s0, 31
	s_waitcnt vmcnt(1)
	v_or_b32_e32 v48, s2, v1
	v_lshl_add_u64 v[2:3], s[0:1], 2, v[22:23]
	v_mad_i64_i32 v[4:5], s[8:9], v48, s12, v[2:3]
	global_load_dwordx4 v[36:39], v[4:5], off nt
	v_or_b32_e32 v4, 8, v48
	v_mad_i64_i32 v[4:5], s[8:9], v4, s12, v[2:3]
	global_load_dwordx4 v[40:43], v[4:5], off nt
	v_or_b32_e32 v4, 16, v48
	v_mad_i64_i32 v[4:5], s[8:9], v4, s12, v[2:3]
	global_load_dwordx4 v[44:47], v[4:5], off nt
	v_or_b32_e32 v4, 24, v48
	v_mad_i64_i32 v[4:5], s[8:9], v4, s12, v[2:3]
	global_load_dwordx4 v[18:21], v[4:5], off nt
	v_or_b32_e32 v4, 32, v48
	v_mad_i64_i32 v[4:5], s[8:9], v4, s12, v[2:3]
	global_load_dwordx4 v[14:17], v[4:5], off nt
	v_or_b32_e32 v4, 40, v48
	v_mad_i64_i32 v[4:5], s[8:9], v4, s12, v[2:3]
	global_load_dwordx4 v[10:13], v[4:5], off nt
	v_or_b32_e32 v4, 48, v48
	v_ashrrev_i32_e32 v49, 31, v48
	v_mad_i64_i32 v[4:5], s[8:9], v4, s12, v[2:3]
	global_load_dwordx4 v[6:9], v[4:5], off nt
	v_or_b32_e32 v4, 56, v48
	v_lshl_add_u64 v[48:49], v[48:49], 2, s[10:11]
	global_load_dword v48, v[48:49], off
	v_mad_i64_i32 v[2:3], s[8:9], v4, s12, v[2:3]
	global_load_dwordx4 v[2:5], v[2:3], off nt
	v_add_u32_e32 v35, 0x420, v34
	s_ashr_i32 s3, s2, 31
	s_add_i32 s6, s6, s7
	s_add_i32 s4, s4, s5
	s_cmpk_lt_i32 s6, 0x1400
	s_waitcnt vmcnt(1)
	v_pk_mul_f32 v[36:37], v[36:37], v[48:49] op_sel_hi:[1,0]
	v_pk_mul_f32 v[38:39], v[38:39], v[48:49] op_sel_hi:[1,0]
	ds_write2_b32 v34, v36, v37 offset1:1
	ds_write2_b32 v34, v38, v39 offset0:2 offset1:3
	v_or_b32_e32 v36, s2, v26
	v_ashrrev_i32_e32 v37, 31, v36
	v_lshl_add_u64 v[36:37], v[36:37], 2, s[10:11]
	global_load_dword v36, v[36:37], off
	s_waitcnt vmcnt(0)
	v_pk_mul_f32 v[38:39], v[42:43], v[36:37] op_sel_hi:[1,0]
	v_pk_mul_f32 v[36:37], v[40:41], v[36:37] op_sel_hi:[1,0]
	ds_write2_b32 v35, v36, v37 offset1:1
	v_or_b32_e32 v36, s2, v27
	v_ashrrev_i32_e32 v37, 31, v36
	v_lshl_add_u64 v[36:37], v[36:37], 2, s[10:11]
	global_load_dword v36, v[36:37], off
	v_add_u32_e32 v35, 0x428, v34
	ds_write2_b32 v35, v38, v39 offset1:1
	v_add_u32_e32 v35, 0x840, v34
	s_waitcnt vmcnt(0)
	v_pk_mul_f32 v[38:39], v[46:47], v[36:37] op_sel_hi:[1,0]
	v_pk_mul_f32 v[36:37], v[44:45], v[36:37] op_sel_hi:[1,0]
	ds_write2_b32 v35, v36, v37 offset1:1
	v_or_b32_e32 v36, s2, v28
	v_ashrrev_i32_e32 v37, 31, v36
	v_lshl_add_u64 v[36:37], v[36:37], 2, s[10:11]
	global_load_dword v36, v[36:37], off
	v_add_u32_e32 v35, 0x848, v34
	ds_write2_b32 v35, v38, v39 offset1:1
	v_add_u32_e32 v35, 0xc60, v34
	v_add_u32_e32 v38, s0, v1
	v_ashrrev_i32_e32 v39, 31, v38
	v_lshlrev_b64 v[40:41], 11, v[38:39]
	s_waitcnt vmcnt(0)
	v_pk_mul_f32 v[18:19], v[18:19], v[36:37] op_sel_hi:[1,0]
	v_pk_mul_f32 v[20:21], v[20:21], v[36:37] op_sel_hi:[1,0]
	ds_write2_b32 v35, v18, v19 offset1:1
	v_add_u32_e32 v18, 0xc68, v34
	ds_write2_b32 v18, v20, v21 offset1:1
	v_or_b32_e32 v18, s2, v29
	v_ashrrev_i32_e32 v19, 31, v18
	v_lshl_add_u64 v[18:19], v[18:19], 2, s[10:11]
	global_load_dword v18, v[18:19], off
	s_waitcnt vmcnt(0)
	v_pk_mul_f32 v[16:17], v[16:17], v[18:19] op_sel_hi:[1,0]
	v_pk_mul_f32 v[14:15], v[14:15], v[18:19] op_sel_hi:[1,0]
	v_add_u32_e32 v18, 0x1080, v34
	ds_write2_b32 v18, v14, v15 offset1:1
	v_add_u32_e32 v14, 0x1088, v34
	ds_write2_b32 v14, v16, v17 offset1:1
	v_or_b32_e32 v14, s2, v30
	v_ashrrev_i32_e32 v15, 31, v14
	v_lshl_add_u64 v[14:15], v[14:15], 2, s[10:11]
	global_load_dword v14, v[14:15], off
	s_waitcnt vmcnt(0)
	v_pk_mul_f32 v[12:13], v[12:13], v[14:15] op_sel_hi:[1,0]
	v_pk_mul_f32 v[10:11], v[10:11], v[14:15] op_sel_hi:[1,0]
	v_add_u32_e32 v14, 0x14a0, v34
	ds_write2_b32 v14, v10, v11 offset1:1
	v_add_u32_e32 v10, 0x14a8, v34
	ds_write2_b32 v10, v12, v13 offset1:1
	v_or_b32_e32 v10, s2, v31
	v_ashrrev_i32_e32 v11, 31, v10
	v_lshl_add_u64 v[10:11], v[10:11], 2, s[10:11]
	global_load_dword v10, v[10:11], off
	s_waitcnt vmcnt(0)
	v_pk_mul_f32 v[8:9], v[8:9], v[10:11] op_sel_hi:[1,0]
	v_pk_mul_f32 v[6:7], v[6:7], v[10:11] op_sel_hi:[1,0]
	v_add_u32_e32 v10, 0x18c0, v34
	ds_write2_b32 v10, v6, v7 offset1:1
	v_add_u32_e32 v6, 0x18c8, v34
	ds_write2_b32 v6, v8, v9 offset1:1
	v_or_b32_e32 v6, s2, v32
	v_ashrrev_i32_e32 v7, 31, v6
	v_lshl_add_u64 v[6:7], v[6:7], 2, s[10:11]
	global_load_dword v6, v[6:7], off
	s_waitcnt vmcnt(0)
	v_pk_mul_f32 v[4:5], v[4:5], v[6:7] op_sel_hi:[1,0]
	v_pk_mul_f32 v[2:3], v[2:3], v[6:7] op_sel_hi:[1,0]
	v_add_u32_e32 v6, 0x1ce0, v34
	ds_write2_b32 v6, v2, v3 offset1:1
	v_add_u32_e32 v2, 0x1ce8, v34
	ds_write2_b32 v2, v4, v5 offset1:1
	s_waitcnt lgkmcnt(0)
	ds_read2_b32 v[8:9], v33 offset0:33 offset1:41
	ds_read2_b32 v[10:11], v33 offset1:8
	ds_read2_b32 v[12:13], v33 offset0:66 offset1:74
	ds_read2_b32 v[14:15], v33 offset0:99 offset1:107
	ds_read2_b32 v[16:17], v33 offset0:132 offset1:140
	ds_read2_b32 v[18:19], v33 offset0:165 offset1:173
	ds_read2_b32 v[20:21], v33 offset0:198 offset1:206
	ds_read2_b32 v[36:37], v33 offset0:231 offset1:239
	v_lshl_add_u64 v[6:7], s[2:3], 1, v[24:25]
	s_waitcnt lgkmcnt(6)
	v_cvt_pk_bf16_f32 v2, v10, v8
	s_waitcnt lgkmcnt(4)
	v_cvt_pk_bf16_f32 v3, v12, v14
	s_waitcnt lgkmcnt(2)
	v_cvt_pk_bf16_f32 v4, v16, v18
	s_waitcnt lgkmcnt(0)
	v_cvt_pk_bf16_f32 v5, v20, v36
	v_lshl_add_u64 v[40:41], v[6:7], 0, v[40:41]
	v_add_u32_e32 v8, 8, v38
	global_store_dwordx4 v[40:41], v[2:5], off nt
	v_add_u32_e32 v40, 16, v38
	v_ashrrev_i32_e32 v41, 31, v40
	v_cvt_pk_bf16_f32 v2, v11, v9
	v_ashrrev_i32_e32 v9, 31, v8
	v_lshlrev_b64 v[8:9], 11, v[8:9]
	v_cvt_pk_bf16_f32 v3, v13, v15
	v_cvt_pk_bf16_f32 v4, v17, v19
	v_cvt_pk_bf16_f32 v5, v21, v37
	v_lshl_add_u64 v[8:9], v[6:7], 0, v[8:9]
	global_store_dwordx4 v[8:9], v[2:5], off nt
	ds_read2_b32 v[8:9], v33 offset0:49 offset1:57
	ds_read2_b32 v[10:11], v33 offset0:16 offset1:24
	ds_read2_b32 v[12:13], v33 offset0:82 offset1:90
	ds_read2_b32 v[14:15], v33 offset0:115 offset1:123
	ds_read2_b32 v[16:17], v33 offset0:148 offset1:156
	ds_read2_b32 v[18:19], v33 offset0:181 offset1:189
	ds_read2_b32 v[20:21], v33 offset0:214 offset1:222
	ds_read2_b32 v[36:37], v33 offset0:247 offset1:255
	v_lshlrev_b64 v[40:41], 11, v[40:41]
	s_waitcnt lgkmcnt(6)
	v_cvt_pk_bf16_f32 v2, v10, v8
	s_waitcnt lgkmcnt(4)
	v_cvt_pk_bf16_f32 v3, v12, v14
	s_waitcnt lgkmcnt(2)
	v_cvt_pk_bf16_f32 v4, v16, v18
	s_waitcnt lgkmcnt(0)
	v_cvt_pk_bf16_f32 v5, v20, v36
	v_lshl_add_u64 v[40:41], v[6:7], 0, v[40:41]
	v_add_u32_e32 v8, 24, v38
	global_store_dwordx4 v[40:41], v[2:5], off nt
	s_nop 1
	v_cvt_pk_bf16_f32 v2, v11, v9
	v_ashrrev_i32_e32 v9, 31, v8
	v_lshlrev_b64 v[8:9], 11, v[8:9]
	v_cvt_pk_bf16_f32 v3, v13, v15
	v_cvt_pk_bf16_f32 v4, v17, v19
	v_cvt_pk_bf16_f32 v5, v21, v37
	v_lshl_add_u64 v[6:7], v[6:7], 0, v[8:9]
	global_store_dwordx4 v[6:7], v[2:5], off nt
	s_waitcnt lgkmcnt(0)
	s_cbranch_scc1 .LBB0_1263

; #define LAS __attribute__((address_space(3)))
; __device__ __forceinline__ unsigned pk2(float lo, float hi) { f32x2_t v = {lo, hi}; bf16x2_t b = __builtin_convertvector(v, bf16x2_t); return __builtin_bit_cast(unsigned, b); }
; __device__ __forceinline__ void transpose_item(const float* W, int K, int N, bf16* WT, const float* scale, LAS float* scr, int item, int lane) {
;     ...
;         const int q = lane & 7, r = lane >> 3;
;         f32x4 v[8];
; #pragma unroll
;         for (int i = 0; i < 8; ++i) v[i] = *(const f32x4*)(W + (size_t)(k0 + 8 * i + r) * N + n0 + 4 * q);
; #pragma unroll
;         for (int i = 0; i < 8; ++i) { const int kk = 8 * i + r; f32x4 x = v[i]; if (scale) x = x * scale[k0 + kk];
;             scr[kk * 33 + 4 * q + 0] = x[0]; scr[kk * 33 + 4 * q + 1] = x[1]; scr[kk * 33 + 4 * q + 2] = x[2]; scr[kk * 33 + 4 * q + 3] = x[3]; }
;     }
;     asm volatile("s_waitcnt lgkmcnt(0)" ::: "memory");
;     const int c = lane & 7;
; #pragma unroll
;     for (int j = 0; j < 4; ++j) { const int n = (lane >> 3) + 8 * j; const LAS float* s = scr + (8 * c) * 33 + n;
;         v4u o; o.x = pk2(s[0 * 33], s[1 * 33]); o.y = pk2(s[2 * 33], s[3 * 33]); o.z = pk2(s[4 * 33], s[5 * 33]); o.w = pk2(s[6 * 33], s[7 * 33]);
;         *(v4u*)(WT + (size_t)(n0 + n) * K + k0 + 8 * c) = o; }
;     asm volatile("s_waitcnt lgkmcnt(0)" ::: "memory");
.LBB0_1266:
	s_ashr_i32 s2, s8, 31
	s_lshr_b32 s2, s2, 27
	s_add_i32 s2, s8, s2
	s_ashr_i32 s2, s2, 5
	s_lshl_b32 s4, s2, 6
	s_lshl_b32 s2, s2, 10
	s_sub_i32 s2, s6, s2
	s_waitcnt vmcnt(24)
	v_or_b32_e32 v38, s4, v1
	s_ashr_i32 s3, s2, 31
	s_waitcnt vmcnt(22)
	v_ashrrev_i32_e32 v39, 31, v38
	v_or_b32_e32 v6, 8, v38
	v_lshl_add_u64 v[18:19], s[2:3], 2, v[14:15]
	v_lshlrev_b64 v[2:3], 12, v[38:39]
	v_ashrrev_i32_e32 v7, 31, v6
	v_lshl_add_u64 v[2:3], v[18:19], 0, v[2:3]
	v_lshlrev_b64 v[6:7], 12, v[6:7]
	v_or_b32_e32 v10, 16, v38
	global_load_dwordx4 v[2:5], v[2:3], off nt
	v_lshl_add_u64 v[6:7], v[18:19], 0, v[6:7]
	v_ashrrev_i32_e32 v11, 31, v10
	global_load_dwordx4 v[6:9], v[6:7], off nt
	v_lshlrev_b64 v[10:11], 12, v[10:11]
	v_or_b32_e32 v22, 24, v38
	v_lshl_add_u64 v[10:11], v[18:19], 0, v[10:11]
	v_ashrrev_i32_e32 v23, 31, v22
	global_load_dwordx4 v[10:13], v[10:11], off nt
	v_lshlrev_b64 v[22:23], 12, v[22:23]
	v_or_b32_e32 v26, 32, v38
	v_lshl_add_u64 v[22:23], v[18:19], 0, v[22:23]
	v_ashrrev_i32_e32 v27, 31, v26
	global_load_dwordx4 v[22:25], v[22:23], off nt
	v_lshlrev_b64 v[26:27], 12, v[26:27]
	v_or_b32_e32 v30, 40, v38
	v_lshl_add_u64 v[26:27], v[18:19], 0, v[26:27]
	v_ashrrev_i32_e32 v31, 31, v30
	global_load_dwordx4 v[26:29], v[26:27], off nt
	v_lshlrev_b64 v[30:31], 12, v[30:31]
	v_or_b32_e32 v34, 48, v38
	v_lshl_add_u64 v[30:31], v[18:19], 0, v[30:31]
	v_ashrrev_i32_e32 v35, 31, v34
	global_load_dwordx4 v[30:33], v[30:31], off nt
	v_lshlrev_b64 v[34:35], 12, v[34:35]
	v_or_b32_e32 v38, 56, v38
	v_lshl_add_u64 v[34:35], v[18:19], 0, v[34:35]
	v_ashrrev_i32_e32 v39, 31, v38
	global_load_dwordx4 v[34:37], v[34:35], off nt
	v_lshlrev_b64 v[38:39], 12, v[38:39]
	v_lshl_add_u64 v[18:19], v[18:19], 0, v[38:39]
	global_load_dwordx4 v[38:41], v[18:19], off nt
	s_ashr_i32 s5, s4, 31
	s_add_i32 s8, s8, s9
	s_add_i32 s6, s6, s7
	s_cmpk_lt_i32 s8, 0x200
	s_waitcnt vmcnt(7)
	ds_write2_b32 v21, v2, v3 offset1:1
	ds_write2_b32 v21, v4, v5 offset0:2 offset1:3
	v_add_u32_e32 v2, 0x420, v21
	s_waitcnt vmcnt(6)
	ds_write2_b32 v2, v6, v7 offset1:1
	v_add_u32_e32 v2, 0x428, v21
	ds_write2_b32 v2, v8, v9 offset1:1
	v_add_u32_e32 v2, 0x840, v21
	v_lshl_add_u64 v[6:7], s[4:5], 1, v[16:17]
	s_waitcnt vmcnt(5)
	ds_write2_b32 v2, v10, v11 offset1:1
	v_add_u32_e32 v2, 0x848, v21
	ds_write2_b32 v2, v12, v13 offset1:1
	v_add_u32_e32 v2, 0xc60, v21
	s_waitcnt vmcnt(4)
	ds_write2_b32 v2, v22, v23 offset1:1
	v_add_u32_e32 v2, 0xc68, v21
	ds_write2_b32 v2, v24, v25 offset1:1
	v_add_u32_e32 v2, 0x1080, v21
	s_waitcnt vmcnt(3)
	ds_write2_b32 v2, v26, v27 offset1:1
	v_add_u32_e32 v2, 0x1088, v21
	ds_write2_b32 v2, v28, v29 offset1:1
	v_add_u32_e32 v2, 0x14a0, v21
	s_waitcnt vmcnt(2)
	ds_write2_b32 v2, v30, v31 offset1:1
	v_add_u32_e32 v2, 0x14a8, v21
	ds_write2_b32 v2, v32, v33 offset1:1
	v_add_u32_e32 v2, 0x18c0, v21
	v_add_u32_e32 v30, s2, v1
	s_waitcnt vmcnt(1)
	ds_write2_b32 v2, v34, v35 offset1:1
	v_add_u32_e32 v2, 0x18c8, v21
	ds_write2_b32 v2, v36, v37 offset1:1
	v_add_u32_e32 v2, 0x1ce0, v21
	s_waitcnt vmcnt(0)
	ds_write2_b32 v2, v38, v39 offset1:1
	v_add_u32_e32 v2, 0x1ce8, v21
	ds_write2_b32 v2, v40, v41 offset1:1
	s_waitcnt lgkmcnt(0)
	ds_read2_b32 v[8:9], v20 offset0:33 offset1:41
	ds_read2_b32 v[10:11], v20 offset1:8
	ds_read2_b32 v[12:13], v20 offset0:66 offset1:74
	ds_read2_b32 v[18:19], v20 offset0:99 offset1:107
	ds_read2_b32 v[22:23], v20 offset0:132 offset1:140
	ds_read2_b32 v[24:25], v20 offset0:165 offset1:173
	ds_read2_b32 v[26:27], v20 offset0:198 offset1:206
	ds_read2_b32 v[28:29], v20 offset0:231 offset1:239
	v_ashrrev_i32_e32 v31, 31, v30
	v_lshlrev_b64 v[32:33], 11, v[30:31]
	s_waitcnt lgkmcnt(6)
	v_cvt_pk_bf16_f32 v2, v10, v8
	s_waitcnt lgkmcnt(4)
	v_cvt_pk_bf16_f32 v3, v12, v18
	s_waitcnt lgkmcnt(2)
	v_cvt_pk_bf16_f32 v4, v22, v24
	s_waitcnt lgkmcnt(0)
	v_cvt_pk_bf16_f32 v5, v26, v28
	v_lshl_add_u64 v[32:33], v[6:7], 0, v[32:33]
	v_add_u32_e32 v8, 8, v30
	global_store_dwordx4 v[32:33], v[2:5], off nt
	v_add_u32_e32 v32, 16, v30
	v_ashrrev_i32_e32 v33, 31, v32
	v_cvt_pk_bf16_f32 v2, v11, v9
	v_ashrrev_i32_e32 v9, 31, v8
	v_lshlrev_b64 v[8:9], 11, v[8:9]
	v_cvt_pk_bf16_f32 v3, v13, v19
	v_cvt_pk_bf16_f32 v4, v23, v25
	v_cvt_pk_bf16_f32 v5, v27, v29
	v_lshl_add_u64 v[8:9], v[6:7], 0, v[8:9]
	global_store_dwordx4 v[8:9], v[2:5], off nt
	ds_read2_b32 v[8:9], v20 offset0:49 offset1:57
	ds_read2_b32 v[10:11], v20 offset0:16 offset1:24
	ds_read2_b32 v[12:13], v20 offset0:82 offset1:90
	ds_read2_b32 v[18:19], v20 offset0:115 offset1:123
	ds_read2_b32 v[22:23], v20 offset0:148 offset1:156
	ds_read2_b32 v[24:25], v20 offset0:181 offset1:189
	ds_read2_b32 v[26:27], v20 offset0:214 offset1:222
	ds_read2_b32 v[28:29], v20 offset0:247 offset1:255
	v_lshlrev_b64 v[32:33], 11, v[32:33]
	s_waitcnt lgkmcnt(6)
	v_cvt_pk_bf16_f32 v2, v10, v8
	s_waitcnt lgkmcnt(4)
	v_cvt_pk_bf16_f32 v3, v12, v18
	s_waitcnt lgkmcnt(2)
	v_cvt_pk_bf16_f32 v4, v22, v24
	s_waitcnt lgkmcnt(0)
	v_cvt_pk_bf16_f32 v5, v26, v28
	v_lshl_add_u64 v[32:33], v[6:7], 0, v[32:33]
	v_add_u32_e32 v8, 24, v30
	global_store_dwordx4 v[32:33], v[2:5], off nt
	s_nop 1
	v_cvt_pk_bf16_f32 v2, v11, v9
	v_ashrrev_i32_e32 v9, 31, v8
	v_lshlrev_b64 v[8:9], 11, v[8:9]
	v_cvt_pk_bf16_f32 v3, v13, v19
	v_cvt_pk_bf16_f32 v4, v23, v25
	v_cvt_pk_bf16_f32 v5, v27, v29
	v_lshl_add_u64 v[6:7], v[6:7], 0, v[8:9]
	global_store_dwordx4 v[6:7], v[2:5], off nt
	s_waitcnt lgkmcnt(0)
	s_cbranch_scc1 .LBB0_1266
	v_readlane_b32 s50, v255, 24
	v_readlane_b32 s51, v255, 25

; #define LAS __attribute__((address_space(3)))
; __device__ __forceinline__ unsigned pk2(float lo, float hi) { f32x2_t v = {lo, hi}; bf16x2_t b = __builtin_convertvector(v, bf16x2_t); return __builtin_bit_cast(unsigned, b); }
; __device__ __forceinline__ void transpose_item(const float* W, int K, int N, bf16* WT, const float* scale, LAS float* scr, int item, int lane) {
;     ...
;         const int q = lane & 7, r = lane >> 3;
;         f32x4 v[8];
; #pragma unroll
;         for (int i = 0; i < 8; ++i) v[i] = *(const f32x4*)(W + (size_t)(k0 + 8 * i + r) * N + n0 + 4 * q);
; #pragma unroll
;         for (int i = 0; i < 8; ++i) { const int kk = 8 * i + r; f32x4 x = v[i]; if (scale) x = x * scale[k0 + kk];
;             scr[kk * 33 + 4 * q + 0] = x[0]; scr[kk * 33 + 4 * q + 1] = x[1]; scr[kk * 33 + 4 * q + 2] = x[2]; scr[kk * 33 + 4 * q + 3] = x[3]; }
;     }
;     asm volatile("s_waitcnt lgkmcnt(0)" ::: "memory");
;     const int c = lane & 7;
; #pragma unroll
;     for (int j = 0; j < 4; ++j) { const int n = (lane >> 3) + 8 * j; const LAS float* s = scr + (8 * c) * 33 + n;
;         v4u o; o.x = pk2(s[0 * 33], s[1 * 33]); o.y = pk2(s[2 * 33], s[3 * 33]); o.z = pk2(s[4 * 33], s[5 * 33]); o.w = pk2(s[6 * 33], s[7 * 33]);
;         *(v4u*)(WT + (size_t)(n0 + n) * K + k0 + 8 * c) = o; }
;     asm volatile("s_waitcnt lgkmcnt(0)" ::: "memory");
.LBB0_1270:
	s_mul_hi_i32 s2, s8, 0x2aaaaaab
	s_lshr_b32 s3, s2, 31
	s_ashr_i32 s2, s2, 4
	s_add_i32 s2, s2, s3
	s_lshl_b32 s4, s2, 6
	s_mulk_i32 s2, 0xf400
	s_add_i32 s2, s6, s2
	s_ashr_i32 s3, s2, 31
	s_waitcnt vmcnt(1)
	v_or_b32_e32 v48, s4, v1
	v_lshl_add_u64 v[2:3], s[2:3], 2, v[22:23]
	v_mad_i64_i32 v[4:5], s[10:11], v48, s14, v[2:3]
	global_load_dwordx4 v[36:39], v[4:5], off nt
	v_or_b32_e32 v4, 8, v48
	v_mad_i64_i32 v[4:5], s[10:11], v4, s14, v[2:3]
	global_load_dwordx4 v[40:43], v[4:5], off nt
	v_or_b32_e32 v4, 16, v48
	v_mad_i64_i32 v[4:5], s[10:11], v4, s14, v[2:3]
	global_load_dwordx4 v[44:47], v[4:5], off nt
	v_or_b32_e32 v4, 24, v48
	v_mad_i64_i32 v[4:5], s[10:11], v4, s14, v[2:3]
	global_load_dwordx4 v[18:21], v[4:5], off nt
	v_or_b32_e32 v4, 32, v48
	v_mad_i64_i32 v[4:5], s[10:11], v4, s14, v[2:3]
	global_load_dwordx4 v[14:17], v[4:5], off nt
	v_or_b32_e32 v4, 40, v48
	v_mad_i64_i32 v[4:5], s[10:11], v4, s14, v[2:3]
	global_load_dwordx4 v[10:13], v[4:5], off nt
	v_or_b32_e32 v4, 48, v48
	v_ashrrev_i32_e32 v49, 31, v48
	v_mad_i64_i32 v[4:5], s[10:11], v4, s14, v[2:3]
	global_load_dwordx4 v[6:9], v[4:5], off nt
	v_or_b32_e32 v4, 56, v48
	v_lshl_add_u64 v[48:49], v[48:49], 2, s[12:13]
	global_load_dword v48, v[48:49], off
	v_mad_i64_i32 v[2:3], s[10:11], v4, s14, v[2:3]
	global_load_dwordx4 v[2:5], v[2:3], off nt
	v_add_u32_e32 v35, 0x420, v34
	s_ashr_i32 s5, s4, 31
	s_add_i32 s8, s8, s9
	s_add_i32 s6, s6, s7
	s_cmpk_lt_i32 s8, 0x600
	s_waitcnt vmcnt(1)
	v_pk_mul_f32 v[36:37], v[36:37], v[48:49] op_sel_hi:[1,0]
	v_pk_mul_f32 v[38:39], v[38:39], v[48:49] op_sel_hi:[1,0]
	ds_write2_b32 v34, v36, v37 offset1:1
	ds_write2_b32 v34, v38, v39 offset0:2 offset1:3
	v_or_b32_e32 v36, s4, v26
	v_ashrrev_i32_e32 v37, 31, v36
	v_lshl_add_u64 v[36:37], v[36:37], 2, s[12:13]
	global_load_dword v36, v[36:37], off
	s_waitcnt vmcnt(0)
	v_pk_mul_f32 v[38:39], v[42:43], v[36:37] op_sel_hi:[1,0]
	v_pk_mul_f32 v[36:37], v[40:41], v[36:37] op_sel_hi:[1,0]
	ds_write2_b32 v35, v36, v37 offset1:1
	v_or_b32_e32 v36, s4, v27
	v_ashrrev_i32_e32 v37, 31, v36
	v_lshl_add_u64 v[36:37], v[36:37], 2, s[12:13]
	global_load_dword v36, v[36:37], off
	v_add_u32_e32 v35, 0x428, v34
	ds_write2_b32 v35, v38, v39 offset1:1
	v_add_u32_e32 v35, 0x840, v34
	s_waitcnt vmcnt(0)
	v_pk_mul_f32 v[38:39], v[46:47], v[36:37] op_sel_hi:[1,0]
	v_pk_mul_f32 v[36:37], v[44:45], v[36:37] op_sel_hi:[1,0]
	ds_write2_b32 v35, v36, v37 offset1:1
	v_or_b32_e32 v36, s4, v28
	v_ashrrev_i32_e32 v37, 31, v36
	v_lshl_add_u64 v[36:37], v[36:37], 2, s[12:13]
	global_load_dword v36, v[36:37], off
	v_add_u32_e32 v35, 0x848, v34
	ds_write2_b32 v35, v38, v39 offset1:1
	v_add_u32_e32 v35, 0xc60, v34
	v_add_u32_e32 v38, s2, v1
	v_ashrrev_i32_e32 v39, 31, v38
	v_lshlrev_b64 v[40:41], 11, v[38:39]
	s_waitcnt vmcnt(0)
	v_pk_mul_f32 v[18:19], v[18:19], v[36:37] op_sel_hi:[1,0]
	v_pk_mul_f32 v[20:21], v[20:21], v[36:37] op_sel_hi:[1,0]
	ds_write2_b32 v35, v18, v19 offset1:1
	v_add_u32_e32 v18, 0xc68, v34
	ds_write2_b32 v18, v20, v21 offset1:1
	v_or_b32_e32 v18, s4, v29
	v_ashrrev_i32_e32 v19, 31, v18
	v_lshl_add_u64 v[18:19], v[18:19], 2, s[12:13]
	global_load_dword v18, v[18:19], off
	s_waitcnt vmcnt(0)
	v_pk_mul_f32 v[16:17], v[16:17], v[18:19] op_sel_hi:[1,0]
	v_pk_mul_f32 v[14:15], v[14:15], v[18:19] op_sel_hi:[1,0]
	v_add_u32_e32 v18, 0x1080, v34
	ds_write2_b32 v18, v14, v15 offset1:1
	v_add_u32_e32 v14, 0x1088, v34
	ds_write2_b32 v14, v16, v17 offset1:1
	v_or_b32_e32 v14, s4, v30
	v_ashrrev_i32_e32 v15, 31, v14
	v_lshl_add_u64 v[14:15], v[14:15], 2, s[12:13]
	global_load_dword v14, v[14:15], off
	s_waitcnt vmcnt(0)
	v_pk_mul_f32 v[12:13], v[12:13], v[14:15] op_sel_hi:[1,0]
	v_pk_mul_f32 v[10:11], v[10:11], v[14:15] op_sel_hi:[1,0]
	v_add_u32_e32 v14, 0x14a0, v34
	ds_write2_b32 v14, v10, v11 offset1:1
	v_add_u32_e32 v10, 0x14a8, v34
	ds_write2_b32 v10, v12, v13 offset1:1
	v_or_b32_e32 v10, s4, v31
	v_ashrrev_i32_e32 v11, 31, v10
	v_lshl_add_u64 v[10:11], v[10:11], 2, s[12:13]
	global_load_dword v10, v[10:11], off
	s_waitcnt vmcnt(0)
	v_pk_mul_f32 v[8:9], v[8:9], v[10:11] op_sel_hi:[1,0]
	v_pk_mul_f32 v[6:7], v[6:7], v[10:11] op_sel_hi:[1,0]
	v_add_u32_e32 v10, 0x18c0, v34
	ds_write2_b32 v10, v6, v7 offset1:1
	v_add_u32_e32 v6, 0x18c8, v34
	ds_write2_b32 v6, v8, v9 offset1:1
	v_or_b32_e32 v6, s4, v32
	v_ashrrev_i32_e32 v7, 31, v6
	v_lshl_add_u64 v[6:7], v[6:7], 2, s[12:13]
	global_load_dword v6, v[6:7], off
	s_waitcnt vmcnt(0)
	v_pk_mul_f32 v[4:5], v[4:5], v[6:7] op_sel_hi:[1,0]
	v_pk_mul_f32 v[2:3], v[2:3], v[6:7] op_sel_hi:[1,0]
	v_add_u32_e32 v6, 0x1ce0, v34
	ds_write2_b32 v6, v2, v3 offset1:1
	v_add_u32_e32 v2, 0x1ce8, v34
	ds_write2_b32 v2, v4, v5 offset1:1
	s_waitcnt lgkmcnt(0)
	ds_read2_b32 v[8:9], v33 offset0:33 offset1:41
	ds_read2_b32 v[10:11], v33 offset1:8
	ds_read2_b32 v[12:13], v33 offset0:66 offset1:74
	ds_read2_b32 v[14:15], v33 offset0:99 offset1:107
	ds_read2_b32 v[16:17], v33 offset0:132 offset1:140
	ds_read2_b32 v[18:19], v33 offset0:165 offset1:173
	ds_read2_b32 v[20:21], v33 offset0:198 offset1:206
	ds_read2_b32 v[36:37], v33 offset0:231 offset1:239
	v_lshl_add_u64 v[6:7], s[4:5], 1, v[24:25]
	s_waitcnt lgkmcnt(6)
	v_cvt_pk_bf16_f32 v2, v10, v8
	s_waitcnt lgkmcnt(4)
	v_cvt_pk_bf16_f32 v3, v12, v14
	s_waitcnt lgkmcnt(2)
	v_cvt_pk_bf16_f32 v4, v16, v18
	s_waitcnt lgkmcnt(0)
	v_cvt_pk_bf16_f32 v5, v20, v36
	v_lshl_add_u64 v[40:41], v[6:7], 0, v[40:41]
	v_add_u32_e32 v8, 8, v38
	global_store_dwordx4 v[40:41], v[2:5], off nt
	v_add_u32_e32 v40, 16, v38
	v_ashrrev_i32_e32 v41, 31, v40
	v_cvt_pk_bf16_f32 v2, v11, v9
	v_ashrrev_i32_e32 v9, 31, v8
	v_lshlrev_b64 v[8:9], 11, v[8:9]
	v_cvt_pk_bf16_f32 v3, v13, v15
	v_cvt_pk_bf16_f32 v4, v17, v19
	v_cvt_pk_bf16_f32 v5, v21, v37
	v_lshl_add_u64 v[8:9], v[6:7], 0, v[8:9]
	global_store_dwordx4 v[8:9], v[2:5], off nt
	ds_read2_b32 v[8:9], v33 offset0:49 offset1:57
	ds_read2_b32 v[10:11], v33 offset0:16 offset1:24
	ds_read2_b32 v[12:13], v33 offset0:82 offset1:90
	ds_read2_b32 v[14:15], v33 offset0:115 offset1:123
	ds_read2_b32 v[16:17], v33 offset0:148 offset1:156
	ds_read2_b32 v[18:19], v33 offset0:181 offset1:189
	ds_read2_b32 v[20:21], v33 offset0:214 offset1:222
	ds_read2_b32 v[36:37], v33 offset0:247 offset1:255
	v_lshlrev_b64 v[40:41], 11, v[40:41]
	s_waitcnt lgkmcnt(6)
	v_cvt_pk_bf16_f32 v2, v10, v8
	s_waitcnt lgkmcnt(4)
	v_cvt_pk_bf16_f32 v3, v12, v14
	s_waitcnt lgkmcnt(2)
	v_cvt_pk_bf16_f32 v4, v16, v18
	s_waitcnt lgkmcnt(0)
	v_cvt_pk_bf16_f32 v5, v20, v36
	v_lshl_add_u64 v[40:41], v[6:7], 0, v[40:41]
	v_add_u32_e32 v8, 24, v38
	global_store_dwordx4 v[40:41], v[2:5], off nt
	s_nop 1
	v_cvt_pk_bf16_f32 v2, v11, v9
	v_ashrrev_i32_e32 v9, 31, v8
	v_lshlrev_b64 v[8:9], 11, v[8:9]
	v_cvt_pk_bf16_f32 v3, v13, v15
	v_cvt_pk_bf16_f32 v4, v17, v19
	v_cvt_pk_bf16_f32 v5, v21, v37
	v_lshl_add_u64 v[6:7], v[6:7], 0, v[8:9]
	global_store_dwordx4 v[6:7], v[2:5], off nt
	s_waitcnt lgkmcnt(0)
	s_cbranch_scc1 .LBB0_1270
	v_readlane_b32 s50, v255, 24
	v_readlane_b32 s51, v255, 25

; #define LAS __attribute__((address_space(3)))
; __device__ __forceinline__ unsigned pk2(float lo, float hi) { f32x2_t v = {lo, hi}; bf16x2_t b = __builtin_convertvector(v, bf16x2_t); return __builtin_bit_cast(unsigned, b); }
; __device__ __forceinline__ void transpose_item(const float* W, int K, int N, bf16* WT, const float* scale, LAS float* scr, int item, int lane) {
;     const int nblk = N / 32, kb = item / nblk, nb = item % nblk, k0 = 64 * kb, n0 = 32 * nb;
;     {
;         const int q = lane & 7, r = lane >> 3;
;         f32x4 v[8];
; #pragma unroll
;         for (int i = 0; i < 8; ++i) v[i] = *(const f32x4*)(W + (size_t)(k0 + 8 * i + r) * N + n0 + 4 * q);
; #pragma unroll
;         for (int i = 0; i < 8; ++i) { const int kk = 8 * i + r; f32x4 x = v[i]; if (scale) x = x * scale[k0 + kk];
;             scr[kk * 33 + 4 * q + 0] = x[0]; scr[kk * 33 + 4 * q + 1] = x[1]; scr[kk * 33 + 4 * q + 2] = x[2]; scr[kk * 33 + 4 * q + 3] = x[3]; }
;     }
;     asm volatile("s_waitcnt lgkmcnt(0)" ::: "memory");
;     const int c = lane & 7;
; #pragma unroll
;     for (int j = 0; j < 4; ++j) { const int n = (lane >> 3) + 8 * j; const LAS float* s = scr + (8 * c) * 33 + n;
;         v4u o; o.x = pk2(s[0 * 33], s[1 * 33]); o.y = pk2(s[2 * 33], s[3 * 33]); o.z = pk2(s[4 * 33], s[5 * 33]); o.w = pk2(s[6 * 33], s[7 * 33]);
;         *(v4u*)(WT + (size_t)(n0 + n) * K + k0 + 8 * c) = o; }
;     asm volatile("s_waitcnt lgkmcnt(0)" ::: "memory");
; }
.LBB0_1274:
	s_ashr_i32 s0, s6, 31
	s_lshr_b32 s0, s0, 27
	s_add_i32 s0, s6, s0
	s_ashr_i32 s0, s0, 5
	s_lshl_b32 s2, s0, 6
	s_lshl_b32 s0, s0, 10
	s_sub_i32 s0, s4, s0
	s_waitcnt vmcnt(24)
	v_or_b32_e32 v38, s2, v1
	s_ashr_i32 s1, s0, 31
	s_waitcnt vmcnt(22)
	v_ashrrev_i32_e32 v39, 31, v38
	v_or_b32_e32 v6, 8, v38
	v_lshl_add_u64 v[18:19], s[0:1], 2, v[14:15]
	v_lshlrev_b64 v[2:3], 12, v[38:39]
	v_ashrrev_i32_e32 v7, 31, v6
	v_lshl_add_u64 v[2:3], v[18:19], 0, v[2:3]
	v_lshlrev_b64 v[6:7], 12, v[6:7]
	v_or_b32_e32 v10, 16, v38
	global_load_dwordx4 v[2:5], v[2:3], off nt
	v_lshl_add_u64 v[6:7], v[18:19], 0, v[6:7]
	v_ashrrev_i32_e32 v11, 31, v10
	global_load_dwordx4 v[6:9], v[6:7], off nt
	v_lshlrev_b64 v[10:11], 12, v[10:11]
	v_or_b32_e32 v22, 24, v38
	v_lshl_add_u64 v[10:11], v[18:19], 0, v[10:11]
	v_ashrrev_i32_e32 v23, 31, v22
	global_load_dwordx4 v[10:13], v[10:11], off nt
	v_lshlrev_b64 v[22:23], 12, v[22:23]
	v_or_b32_e32 v26, 32, v38
	v_lshl_add_u64 v[22:23], v[18:19], 0, v[22:23]
	v_ashrrev_i32_e32 v27, 31, v26
	global_load_dwordx4 v[22:25], v[22:23], off nt
	v_lshlrev_b64 v[26:27], 12, v[26:27]
	v_or_b32_e32 v30, 40, v38
	v_lshl_add_u64 v[26:27], v[18:19], 0, v[26:27]
	v_ashrrev_i32_e32 v31, 31, v30
	global_load_dwordx4 v[26:29], v[26:27], off nt
	v_lshlrev_b64 v[30:31], 12, v[30:31]
	v_or_b32_e32 v34, 48, v38
	v_lshl_add_u64 v[30:31], v[18:19], 0, v[30:31]
	v_ashrrev_i32_e32 v35, 31, v34
	global_load_dwordx4 v[30:33], v[30:31], off nt
	v_lshlrev_b64 v[34:35], 12, v[34:35]
	v_or_b32_e32 v38, 56, v38
	v_lshl_add_u64 v[34:35], v[18:19], 0, v[34:35]
	v_ashrrev_i32_e32 v39, 31, v38
	global_load_dwordx4 v[34:37], v[34:35], off nt
	v_lshlrev_b64 v[38:39], 12, v[38:39]
	v_lshl_add_u64 v[18:19], v[18:19], 0, v[38:39]
	global_load_dwordx4 v[38:41], v[18:19], off nt
	s_ashr_i32 s3, s2, 31
	s_add_i32 s6, s6, s7
	s_add_i32 s4, s4, s5
	s_cmpk_lt_i32 s6, 0x200
	s_waitcnt vmcnt(7)
	ds_write2_b32 v21, v2, v3 offset1:1
	ds_write2_b32 v21, v4, v5 offset0:2 offset1:3
	v_add_u32_e32 v2, 0x420, v21
	s_waitcnt vmcnt(6)
	ds_write2_b32 v2, v6, v7 offset1:1
	v_add_u32_e32 v2, 0x428, v21
	ds_write2_b32 v2, v8, v9 offset1:1
	v_add_u32_e32 v2, 0x840, v21
	v_lshl_add_u64 v[6:7], s[2:3], 1, v[16:17]
	s_waitcnt vmcnt(5)
	ds_write2_b32 v2, v10, v11 offset1:1
	v_add_u32_e32 v2, 0x848, v21
	ds_write2_b32 v2, v12, v13 offset1:1
	v_add_u32_e32 v2, 0xc60, v21
	s_waitcnt vmcnt(4)
	ds_write2_b32 v2, v22, v23 offset1:1
	v_add_u32_e32 v2, 0xc68, v21
	ds_write2_b32 v2, v24, v25 offset1:1
	v_add_u32_e32 v2, 0x1080, v21
	s_waitcnt vmcnt(3)
	ds_write2_b32 v2, v26, v27 offset1:1
	v_add_u32_e32 v2, 0x1088, v21
	ds_write2_b32 v2, v28, v29 offset1:1
	v_add_u32_e32 v2, 0x14a0, v21
	s_waitcnt vmcnt(2)
	ds_write2_b32 v2, v30, v31 offset1:1
	v_add_u32_e32 v2, 0x14a8, v21
	ds_write2_b32 v2, v32, v33 offset1:1
	v_add_u32_e32 v2, 0x18c0, v21
	v_add_u32_e32 v30, s0, v1
	s_waitcnt vmcnt(1)
	ds_write2_b32 v2, v34, v35 offset1:1
	v_add_u32_e32 v2, 0x18c8, v21
	ds_write2_b32 v2, v36, v37 offset1:1
	v_add_u32_e32 v2, 0x1ce0, v21
	s_waitcnt vmcnt(0)
	ds_write2_b32 v2, v38, v39 offset1:1
	v_add_u32_e32 v2, 0x1ce8, v21
	ds_write2_b32 v2, v40, v41 offset1:1
	s_waitcnt lgkmcnt(0)
	ds_read2_b32 v[8:9], v20 offset0:33 offset1:41
	ds_read2_b32 v[10:11], v20 offset1:8
	ds_read2_b32 v[12:13], v20 offset0:66 offset1:74
	ds_read2_b32 v[18:19], v20 offset0:99 offset1:107
	ds_read2_b32 v[22:23], v20 offset0:132 offset1:140
	ds_read2_b32 v[24:25], v20 offset0:165 offset1:173
	ds_read2_b32 v[26:27], v20 offset0:198 offset1:206
	ds_read2_b32 v[28:29], v20 offset0:231 offset1:239
	v_ashrrev_i32_e32 v31, 31, v30
	v_lshlrev_b64 v[32:33], 11, v[30:31]
	s_waitcnt lgkmcnt(6)
	v_cvt_pk_bf16_f32 v2, v10, v8
	s_waitcnt lgkmcnt(4)
	v_cvt_pk_bf16_f32 v3, v12, v18
	s_waitcnt lgkmcnt(2)
	v_cvt_pk_bf16_f32 v4, v22, v24
	s_waitcnt lgkmcnt(0)
	v_cvt_pk_bf16_f32 v5, v26, v28
	v_lshl_add_u64 v[32:33], v[6:7], 0, v[32:33]
	v_add_u32_e32 v8, 8, v30
	global_store_dwordx4 v[32:33], v[2:5], off nt
	v_add_u32_e32 v32, 16, v30
	v_ashrrev_i32_e32 v33, 31, v32
	v_cvt_pk_bf16_f32 v2, v11, v9
	v_ashrrev_i32_e32 v9, 31, v8
	v_lshlrev_b64 v[8:9], 11, v[8:9]
	v_cvt_pk_bf16_f32 v3, v13, v19
	v_cvt_pk_bf16_f32 v4, v23, v25
	v_cvt_pk_bf16_f32 v5, v27, v29
	v_lshl_add_u64 v[8:9], v[6:7], 0, v[8:9]
	global_store_dwordx4 v[8:9], v[2:5], off nt
	ds_read2_b32 v[8:9], v20 offset0:49 offset1:57
	ds_read2_b32 v[10:11], v20 offset0:16 offset1:24
	ds_read2_b32 v[12:13], v20 offset0:82 offset1:90
	ds_read2_b32 v[18:19], v20 offset0:115 offset1:123
	ds_read2_b32 v[22:23], v20 offset0:148 offset1:156
	ds_read2_b32 v[24:25], v20 offset0:181 offset1:189
	ds_read2_b32 v[26:27], v20 offset0:214 offset1:222
	ds_read2_b32 v[28:29], v20 offset0:247 offset1:255
	v_lshlrev_b64 v[32:33], 11, v[32:33]
	s_waitcnt lgkmcnt(6)
	v_cvt_pk_bf16_f32 v2, v10, v8
	s_waitcnt lgkmcnt(4)
	v_cvt_pk_bf16_f32 v3, v12, v18
	s_waitcnt lgkmcnt(2)
	v_cvt_pk_bf16_f32 v4, v22, v24
	s_waitcnt lgkmcnt(0)
	v_cvt_pk_bf16_f32 v5, v26, v28
	v_lshl_add_u64 v[32:33], v[6:7], 0, v[32:33]
	v_add_u32_e32 v8, 24, v30
	global_store_dwordx4 v[32:33], v[2:5], off nt
	s_nop 1
	v_cvt_pk_bf16_f32 v2, v11, v9
	v_ashrrev_i32_e32 v9, 31, v8
	v_lshlrev_b64 v[8:9], 11, v[8:9]
	v_cvt_pk_bf16_f32 v3, v13, v19
	v_cvt_pk_bf16_f32 v4, v23, v25
	v_cvt_pk_bf16_f32 v5, v27, v29
	v_lshl_add_u64 v[6:7], v[6:7], 0, v[8:9]
	global_store_dwordx4 v[6:7], v[2:5], off nt
	s_waitcnt lgkmcnt(0)
	s_cbranch_scc1 .LBB0_1274
	v_readlane_b32 s50, v255, 24
	v_readlane_b32 s51, v255, 25

; #define LAS __attribute__((address_space(3)))
; __device__ __forceinline__ void transpose_item(const float* W, int K, int N, bf16* WT, const float* scale, LAS float* scr, int item, int lane) {
;     const int nblk = N / 32, kb = item / nblk, nb = item % nblk, k0 = 64 * kb, n0 = 32 * nb;
;     {
;         const int q = lane & 7, r = lane >> 3;
;         f32x4 v[8];
; #pragma unroll
;         for (int i = 0; i < 8; ++i) v[i] = *(const f32x4*)(W + (size_t)(k0 + 8 * i + r) * N + n0 + 4 * q);
; #pragma unroll
;         for (int i = 0; i < 8; ++i) { const int kk = 8 * i + r; f32x4 x = v[i]; if (scale) x = x * scale[k0 + kk];
;             scr[kk * 33 + 4 * q + 0] = x[0]; scr[kk * 33 + 4 * q + 1] = x[1]; scr[kk * 33 + 4 * q + 2] = x[2]; scr[kk * 33 + 4 * q + 3] = x[3]; }
;     }
.LBB0_1278:
	s_ashr_i32 s0, s6, 31
	s_lshr_b32 s0, s0, 25
	s_add_i32 s0, s6, s0
	s_ashr_i32 s0, s0, 7
	s_lshl_b32 s2, s0, 6
	s_lshl_b32 s0, s0, 12
	s_sub_i32 s0, s4, s0
	s_waitcnt vmcnt(1)
	v_or_b32_e32 v48, s2, v1
	s_ashr_i32 s1, s0, 31
	v_ashrrev_i32_e32 v49, 31, v48
	v_lshl_add_u64 v[2:3], s[0:1], 2, v[26:27]
	v_lshlrev_b64 v[4:5], 14, v[48:49]
	v_lshl_add_u64 v[4:5], v[2:3], 0, v[4:5]
	global_load_dwordx4 v[30:33], v[4:5], off nt
	v_or_b32_e32 v4, 8, v48
	v_ashrrev_i32_e32 v5, 31, v4
	v_lshlrev_b64 v[4:5], 14, v[4:5]
	v_lshl_add_u64 v[4:5], v[2:3], 0, v[4:5]
	global_load_dwordx4 v[44:47], v[4:5], off nt
	v_or_b32_e32 v4, 16, v48
	v_ashrrev_i32_e32 v5, 31, v4
	v_lshlrev_b64 v[4:5], 14, v[4:5]
	v_lshl_add_u64 v[4:5], v[2:3], 0, v[4:5]
	global_load_dwordx4 v[22:25], v[4:5], off nt
	v_or_b32_e32 v4, 24, v48
	v_ashrrev_i32_e32 v5, 31, v4
	v_lshlrev_b64 v[4:5], 14, v[4:5]
	v_lshl_add_u64 v[4:5], v[2:3], 0, v[4:5]
	global_load_dwordx4 v[18:21], v[4:5], off nt
	v_or_b32_e32 v4, 32, v48
	v_ashrrev_i32_e32 v5, 31, v4
	v_lshlrev_b64 v[4:5], 14, v[4:5]
	v_lshl_add_u64 v[4:5], v[2:3], 0, v[4:5]
	global_load_dwordx4 v[14:17], v[4:5], off nt
	v_or_b32_e32 v4, 40, v48
	v_ashrrev_i32_e32 v5, 31, v4
	v_lshlrev_b64 v[4:5], 14, v[4:5]
	v_lshl_add_u64 v[4:5], v[2:3], 0, v[4:5]
	global_load_dwordx4 v[10:13], v[4:5], off nt
	v_or_b32_e32 v4, 48, v48
	v_ashrrev_i32_e32 v5, 31, v4
	v_lshlrev_b64 v[4:5], 14, v[4:5]
	v_lshl_add_u64 v[4:5], v[2:3], 0, v[4:5]
	global_load_dwordx4 v[6:9], v[4:5], off nt
	v_or_b32_e32 v4, 56, v48
	v_lshl_add_u64 v[48:49], v[48:49], 2, s[8:9]
	global_load_dword v48, v[48:49], off
	v_ashrrev_i32_e32 v5, 31, v4
	v_lshlrev_b64 v[4:5], 14, v[4:5]
	v_lshl_add_u64 v[2:3], v[2:3], 0, v[4:5]
	global_load_dwordx4 v[2:5], v[2:3], off nt
	v_add_u32_e32 v43, 0x420, v42
	s_ashr_i32 s3, s2, 31
	s_add_i32 s6, s6, s7
	s_add_i32 s4, s4, s5
	s_cmpk_lt_i32 s6, 0x800
	s_waitcnt vmcnt(1)
	v_pk_mul_f32 v[30:31], v[30:31], v[48:49] op_sel_hi:[1,0]
	v_pk_mul_f32 v[32:33], v[32:33], v[48:49] op_sel_hi:[1,0]
	ds_write2_b32 v42, v30, v31 offset1:1
	ds_write2_b32 v42, v32, v33 offset0:2 offset1:3
	v_or_b32_e32 v30, s2, v34
	v_ashrrev_i32_e32 v31, 31, v30
	v_lshl_add_u64 v[30:31], v[30:31], 2, s[8:9]
	global_load_dword v32, v[30:31], off
	s_waitcnt vmcnt(0)
	v_pk_mul_f32 v[30:31], v[46:47], v[32:33] op_sel_hi:[1,0]
	v_pk_mul_f32 v[32:33], v[44:45], v[32:33] op_sel_hi:[1,0]
	ds_write2_b32 v43, v32, v33 offset1:1
	v_add_u32_e32 v32, 0x428, v42
	ds_write2_b32 v32, v30, v31 offset1:1
	v_or_b32_e32 v30, s2, v35
	v_ashrrev_i32_e32 v31, 31, v30
	v_lshl_add_u64 v[30:31], v[30:31], 2, s[8:9]
	global_load_dword v30, v[30:31], off
	s_waitcnt vmcnt(0)
	v_pk_mul_f32 v[24:25], v[24:25], v[30:31] op_sel_hi:[1,0]
	v_pk_mul_f32 v[22:23], v[22:23], v[30:31] op_sel_hi:[1,0]
	v_add_u32_e32 v30, 0x840, v42
	ds_write2_b32 v30, v22, v23 offset1:1
	v_add_u32_e32 v22, 0x848, v42
	ds_write2_b32 v22, v24, v25 offset1:1
	v_or_b32_e32 v22, s2, v36
	v_ashrrev_i32_e32 v23, 31, v22
	v_lshl_add_u64 v[22:23], v[22:23], 2, s[8:9]
	global_load_dword v22, v[22:23], off
	v_add_u32_e32 v24, s0, v1
	v_ashrrev_i32_e32 v25, 31, v24
	v_lshlrev_b64 v[30:31], 11, v[24:25]
	s_waitcnt vmcnt(0)
	v_pk_mul_f32 v[20:21], v[20:21], v[22:23] op_sel_hi:[1,0]
	v_pk_mul_f32 v[18:19], v[18:19], v[22:23] op_sel_hi:[1,0]
	v_add_u32_e32 v22, 0xc60, v42
	ds_write2_b32 v22, v18, v19 offset1:1
	v_add_u32_e32 v18, 0xc68, v42
	ds_write2_b32 v18, v20, v21 offset1:1
	v_or_b32_e32 v18, s2, v37
	v_ashrrev_i32_e32 v19, 31, v18
	v_lshl_add_u64 v[18:19], v[18:19], 2, s[8:9]
	global_load_dword v18, v[18:19], off
	s_waitcnt vmcnt(0)
; #define LAS __attribute__((address_space(3)))
; __device__ __forceinline__ unsigned pk2(float lo, float hi) { f32x2_t v = {lo, hi}; bf16x2_t b = __builtin_convertvector(v, bf16x2_t); return __builtin_bit_cast(unsigned, b); }
; __device__ __forceinline__ void transpose_item(const float* W, int K, int N, bf16* WT, const float* scale, LAS float* scr, int item, int lane) {
;     ...
;         for (int i = 0; i < 8; ++i) v[i] = *(const f32x4*)(W + (size_t)(k0 + 8 * i + r) * N + n0 + 4 * q);
; #pragma unroll
;         for (int i = 0; i < 8; ++i) { const int kk = 8 * i + r; f32x4 x = v[i]; if (scale) x = x * scale[k0 + kk];
;             scr[kk * 33 + 4 * q + 0] = x[0]; scr[kk * 33 + 4 * q + 1] = x[1]; scr[kk * 33 + 4 * q + 2] = x[2]; scr[kk * 33 + 4 * q + 3] = x[3]; }
;     }
;     asm volatile("s_waitcnt lgkmcnt(0)" ::: "memory");
;     const int c = lane & 7;
; #pragma unroll
;     for (int j = 0; j < 4; ++j) { const int n = (lane >> 3) + 8 * j; const LAS float* s = scr + (8 * c) * 33 + n;
;         v4u o; o.x = pk2(s[0 * 33], s[1 * 33]); o.y = pk2(s[2 * 33], s[3 * 33]); o.z = pk2(s[4 * 33], s[5 * 33]); o.w = pk2(s[6 * 33], s[7 * 33]);
;         *(v4u*)(WT + (size_t)(n0 + n) * K + k0 + 8 * c) = o; }
;     asm volatile("s_waitcnt lgkmcnt(0)" ::: "memory");
; }
	v_pk_mul_f32 v[16:17], v[16:17], v[18:19] op_sel_hi:[1,0]
	v_pk_mul_f32 v[14:15], v[14:15], v[18:19] op_sel_hi:[1,0]
	v_add_u32_e32 v18, 0x1080, v42
	ds_write2_b32 v18, v14, v15 offset1:1
	v_add_u32_e32 v14, 0x1088, v42
	ds_write2_b32 v14, v16, v17 offset1:1
	v_or_b32_e32 v14, s2, v38
	v_ashrrev_i32_e32 v15, 31, v14
	v_lshl_add_u64 v[14:15], v[14:15], 2, s[8:9]
	global_load_dword v14, v[14:15], off
	s_waitcnt vmcnt(0)
	v_pk_mul_f32 v[12:13], v[12:13], v[14:15] op_sel_hi:[1,0]
	v_pk_mul_f32 v[10:11], v[10:11], v[14:15] op_sel_hi:[1,0]
	v_add_u32_e32 v14, 0x14a0, v42
	ds_write2_b32 v14, v10, v11 offset1:1
	v_add_u32_e32 v10, 0x14a8, v42
	ds_write2_b32 v10, v12, v13 offset1:1
	v_or_b32_e32 v10, s2, v39
	v_ashrrev_i32_e32 v11, 31, v10
	v_lshl_add_u64 v[10:11], v[10:11], 2, s[8:9]
	global_load_dword v10, v[10:11], off
	s_waitcnt vmcnt(0)
	v_pk_mul_f32 v[8:9], v[8:9], v[10:11] op_sel_hi:[1,0]
	v_pk_mul_f32 v[6:7], v[6:7], v[10:11] op_sel_hi:[1,0]
	v_add_u32_e32 v10, 0x18c0, v42
	ds_write2_b32 v10, v6, v7 offset1:1
	v_add_u32_e32 v6, 0x18c8, v42
	ds_write2_b32 v6, v8, v9 offset1:1
	v_or_b32_e32 v6, s2, v40
	v_ashrrev_i32_e32 v7, 31, v6
	v_lshl_add_u64 v[6:7], v[6:7], 2, s[8:9]
	global_load_dword v6, v[6:7], off
	s_waitcnt vmcnt(0)
	v_pk_mul_f32 v[4:5], v[4:5], v[6:7] op_sel_hi:[1,0]
	v_pk_mul_f32 v[2:3], v[2:3], v[6:7] op_sel_hi:[1,0]
	v_add_u32_e32 v6, 0x1ce0, v42
	ds_write2_b32 v6, v2, v3 offset1:1
	v_add_u32_e32 v2, 0x1ce8, v42
	ds_write2_b32 v2, v4, v5 offset1:1
	s_waitcnt lgkmcnt(0)
	ds_read2_b32 v[8:9], v41 offset0:33 offset1:41
	ds_read2_b32 v[10:11], v41 offset1:8
	ds_read2_b32 v[12:13], v41 offset0:66 offset1:74
	ds_read2_b32 v[14:15], v41 offset0:99 offset1:107
	ds_read2_b32 v[16:17], v41 offset0:132 offset1:140
	ds_read2_b32 v[18:19], v41 offset0:165 offset1:173
	ds_read2_b32 v[20:21], v41 offset0:198 offset1:206
	ds_read2_b32 v[22:23], v41 offset0:231 offset1:239
	v_lshl_add_u64 v[6:7], s[2:3], 1, v[28:29]
	s_waitcnt lgkmcnt(6)
	v_cvt_pk_bf16_f32 v2, v10, v8
	s_waitcnt lgkmcnt(4)
	v_cvt_pk_bf16_f32 v3, v12, v14
	s_waitcnt lgkmcnt(2)
	v_cvt_pk_bf16_f32 v4, v16, v18
	s_waitcnt lgkmcnt(0)
	v_cvt_pk_bf16_f32 v5, v20, v22
	v_lshl_add_u64 v[30:31], v[6:7], 0, v[30:31]
	v_add_u32_e32 v8, 8, v24
	global_store_dwordx4 v[30:31], v[2:5], off nt
	v_add_u32_e32 v30, 16, v24
	v_ashrrev_i32_e32 v31, 31, v30
	v_cvt_pk_bf16_f32 v2, v11, v9
	v_ashrrev_i32_e32 v9, 31, v8
	v_lshlrev_b64 v[8:9], 11, v[8:9]
	v_cvt_pk_bf16_f32 v3, v13, v15
	v_cvt_pk_bf16_f32 v4, v17, v19
	v_cvt_pk_bf16_f32 v5, v21, v23
	v_lshl_add_u64 v[8:9], v[6:7], 0, v[8:9]
	global_store_dwordx4 v[8:9], v[2:5], off nt
	ds_read2_b32 v[8:9], v41 offset0:49 offset1:57
	ds_read2_b32 v[10:11], v41 offset0:16 offset1:24
	ds_read2_b32 v[12:13], v41 offset0:82 offset1:90
	ds_read2_b32 v[14:15], v41 offset0:115 offset1:123
	ds_read2_b32 v[16:17], v41 offset0:148 offset1:156
	ds_read2_b32 v[18:19], v41 offset0:181 offset1:189
	ds_read2_b32 v[20:21], v41 offset0:214 offset1:222
	ds_read2_b32 v[22:23], v41 offset0:247 offset1:255
	v_lshlrev_b64 v[30:31], 11, v[30:31]
	s_waitcnt lgkmcnt(6)
	v_cvt_pk_bf16_f32 v2, v10, v8
	s_waitcnt lgkmcnt(4)
	v_cvt_pk_bf16_f32 v3, v12, v14
	s_waitcnt lgkmcnt(2)
	v_cvt_pk_bf16_f32 v4, v16, v18
	s_waitcnt lgkmcnt(0)
	v_cvt_pk_bf16_f32 v5, v20, v22
	v_lshl_add_u64 v[30:31], v[6:7], 0, v[30:31]
	v_add_u32_e32 v8, 24, v24
	global_store_dwordx4 v[30:31], v[2:5], off nt
	s_nop 1
	v_cvt_pk_bf16_f32 v2, v11, v9
	v_ashrrev_i32_e32 v9, 31, v8
	v_lshlrev_b64 v[8:9], 11, v[8:9]
	v_cvt_pk_bf16_f32 v3, v13, v15
	v_cvt_pk_bf16_f32 v4, v17, v19
	v_cvt_pk_bf16_f32 v5, v21, v23
	v_lshl_add_u64 v[6:7], v[6:7], 0, v[8:9]
	global_store_dwordx4 v[6:7], v[2:5], off nt
	s_waitcnt lgkmcnt(0)
	s_cbranch_scc1 .LBB0_1278
